# v15: v12 + KPE row loads in the ukv epilogue issued before the k_nope stores, counted wait
# speedup vs baseline: 1.0076x; 1.0016x over previous
;     __device__ __forceinline__ void operator()(const f32x4 (&acc)[2][2][4][2], const Unit& u, int wr, int wc, int fr, int fq) const {
;     ...
;                 const size_t hs = (size_t)(b * 4 + h) * SEQ + s_;
;                 if (isq) { bf16_t* d = QB + hs * 96;
;                     if (!rope) { *(u32x4*)(d + 8 * fq) = wa; *(u32x4*)(d + 32 + 8 * fq) = wb; }
;                     else if (fq < 2) { *(u32x4*)(d + 64 + 8 * fq) = wa; *(u32x4*)(d + 80 + 8 * fq) = wb; } }
;                 else if (!isv) { bf16_t* d = KB + hs * 96; *(u32x4*)(d + 8 * fq) = wa; *(u32x4*)(d + 32 + 8 * fq) = wb;
;                     *(u32x4*)(d + 64 + 8 * fq) = *(const u32x4*)(KPE + (size_t)row * 32 + 8 * fq); }
.LBB0_469:
	s_andn2_b64 vcc, exec, s[20:21]
	s_cbranch_vccnz .LBB0_471
	s_movk_i32 s2, 0xc0
	v_mad_u64_u32 v[144:145], s[20:21], v138, s2, v[164:165]
	v_mov_b32_e32 v16, v145
	v_mad_u64_u32 v[140:141], s[20:21], v139, s2, v[16:17]
	v_ashrrev_i32_e32 v171, 31, v170
	v_mov_b32_e32 v145, v140
	v_lshlrev_b64 v[140:141], 6, v[170:171]
	v_lshl_add_u64 v[140:141], v[160:161], 0, v[140:141]
	global_load_dwordx4 v[218:221], v[140:141], off
	flat_store_dwordx4 v[144:145], v[130:133]
	flat_store_dwordx4 v[144:145], v[134:137] offset:64
	s_waitcnt vmcnt(2)
	flat_store_dwordx4 v[144:145], v[218:221] offset:128

;     __device__ __forceinline__ void operator()(const f32x4 (&acc)[2][2][4][2], const Unit& u, int wr, int wc, int fr, int fq) const {
;     ...
;                 const size_t hs = (size_t)(b * 4 + h) * SEQ + s_;
;                 if (isq) { bf16_t* d = QB + hs * 96;
;                     if (!rope) { *(u32x4*)(d + 8 * fq) = wa; *(u32x4*)(d + 32 + 8 * fq) = wb; }
;                     else if (fq < 2) { *(u32x4*)(d + 64 + 8 * fq) = wa; *(u32x4*)(d + 80 + 8 * fq) = wb; } }
;                 else if (!isv) { bf16_t* d = KB + hs * 96; *(u32x4*)(d + 8 * fq) = wa; *(u32x4*)(d + 32 + 8 * fq) = wb;
;                     *(u32x4*)(d + 64 + 8 * fq) = *(const u32x4*)(KPE + (size_t)row * 32 + 8 * fq); }
.LBB0_487:
	s_andn2_b64 vcc, exec, s[72:73]
	s_cbranch_vccnz .LBB0_489
	s_movk_i32 s2, 0xc0
	v_mad_u64_u32 v[128:129], s[72:73], v122, s2, v[164:165]
	v_mov_b32_e32 v16, v129
	v_mad_u64_u32 v[124:125], s[72:73], v123, s2, v[16:17]
	v_ashrrev_i32_e32 v131, 31, v130
	v_mov_b32_e32 v129, v124
	v_lshlrev_b64 v[124:125], 6, v[130:131]
	v_lshl_add_u64 v[124:125], v[160:161], 0, v[124:125]
	global_load_dwordx4 v[218:221], v[124:125], off
	flat_store_dwordx4 v[128:129], v[114:117]
	flat_store_dwordx4 v[128:129], v[118:121] offset:64
	s_waitcnt vmcnt(2)
	flat_store_dwordx4 v[128:129], v[218:221] offset:128

;     __device__ __forceinline__ void operator()(const f32x4 (&acc)[2][2][4][2], const Unit& u, int wr, int wc, int fr, int fq) const {
;     ...
;                 const size_t hs = (size_t)(b * 4 + h) * SEQ + s_;
;                 if (isq) { bf16_t* d = QB + hs * 96;
;                     if (!rope) { *(u32x4*)(d + 8 * fq) = wa; *(u32x4*)(d + 32 + 8 * fq) = wb; }
;                     else if (fq < 2) { *(u32x4*)(d + 64 + 8 * fq) = wa; *(u32x4*)(d + 80 + 8 * fq) = wb; } }
;                 else if (!isv) { bf16_t* d = KB + hs * 96; *(u32x4*)(d + 8 * fq) = wa; *(u32x4*)(d + 32 + 8 * fq) = wb;
;                     *(u32x4*)(d + 64 + 8 * fq) = *(const u32x4*)(KPE + (size_t)row * 32 + 8 * fq); }
.LBB0_505:
	s_andn2_b64 vcc, exec, s[72:73]
	s_cbranch_vccnz .LBB0_507
	s_movk_i32 s2, 0xc0
	v_mad_u64_u32 v[112:113], s[72:73], v106, s2, v[164:165]
	v_mov_b32_e32 v16, v113
	v_mad_u64_u32 v[108:109], s[72:73], v107, s2, v[16:17]
	v_ashrrev_i32_e32 v115, 31, v114
	v_mov_b32_e32 v113, v108
	v_lshlrev_b64 v[108:109], 6, v[114:115]
	v_lshl_add_u64 v[108:109], v[160:161], 0, v[108:109]
	global_load_dwordx4 v[218:221], v[108:109], off
	flat_store_dwordx4 v[112:113], v[98:101]
	flat_store_dwordx4 v[112:113], v[102:105] offset:64
	s_waitcnt vmcnt(2)
	flat_store_dwordx4 v[112:113], v[218:221] offset:128

;     __device__ __forceinline__ void operator()(const f32x4 (&acc)[2][2][4][2], const Unit& u, int wr, int wc, int fr, int fq) const {
;     ...
;                 const size_t hs = (size_t)(b * 4 + h) * SEQ + s_;
;                 if (isq) { bf16_t* d = QB + hs * 96;
;                     if (!rope) { *(u32x4*)(d + 8 * fq) = wa; *(u32x4*)(d + 32 + 8 * fq) = wb; }
;                     else if (fq < 2) { *(u32x4*)(d + 64 + 8 * fq) = wa; *(u32x4*)(d + 80 + 8 * fq) = wb; } }
;                 else if (!isv) { bf16_t* d = KB + hs * 96; *(u32x4*)(d + 8 * fq) = wa; *(u32x4*)(d + 32 + 8 * fq) = wb;
;                     *(u32x4*)(d + 64 + 8 * fq) = *(const u32x4*)(KPE + (size_t)row * 32 + 8 * fq); }
.LBB0_523:
	s_andn2_b64 vcc, exec, s[72:73]
	s_cbranch_vccnz .LBB0_525
	s_movk_i32 s2, 0xc0
	v_mad_u64_u32 v[96:97], s[72:73], v90, s2, v[164:165]
	v_mov_b32_e32 v16, v97
	v_mad_u64_u32 v[92:93], s[72:73], v91, s2, v[16:17]
	v_ashrrev_i32_e32 v99, 31, v98
	v_mov_b32_e32 v97, v92
	v_lshlrev_b64 v[92:93], 6, v[98:99]
	v_lshl_add_u64 v[92:93], v[160:161], 0, v[92:93]
	global_load_dwordx4 v[218:221], v[92:93], off
	flat_store_dwordx4 v[96:97], v[82:85]
	flat_store_dwordx4 v[96:97], v[86:89] offset:64
	s_waitcnt vmcnt(2)
	flat_store_dwordx4 v[96:97], v[218:221] offset:128

;     __device__ __forceinline__ void operator()(const f32x4 (&acc)[2][2][4][2], const Unit& u, int wr, int wc, int fr, int fq) const {
;     ...
;                 const size_t hs = (size_t)(b * 4 + h) * SEQ + s_;
;                 if (isq) { bf16_t* d = QB + hs * 96;
;                     if (!rope) { *(u32x4*)(d + 8 * fq) = wa; *(u32x4*)(d + 32 + 8 * fq) = wb; }
;                     else if (fq < 2) { *(u32x4*)(d + 64 + 8 * fq) = wa; *(u32x4*)(d + 80 + 8 * fq) = wb; } }
;                 else if (!isv) { bf16_t* d = KB + hs * 96; *(u32x4*)(d + 8 * fq) = wa; *(u32x4*)(d + 32 + 8 * fq) = wb;
;                     *(u32x4*)(d + 64 + 8 * fq) = *(const u32x4*)(KPE + (size_t)row * 32 + 8 * fq); }
.LBB0_541:
	s_andn2_b64 vcc, exec, s[72:73]
	s_cbranch_vccnz .LBB0_543
	s_movk_i32 s2, 0xc0
	v_mad_u64_u32 v[80:81], s[72:73], v74, s2, v[164:165]
	v_mov_b32_e32 v16, v81
	v_mad_u64_u32 v[76:77], s[72:73], v75, s2, v[16:17]
	v_ashrrev_i32_e32 v83, 31, v82
	v_mov_b32_e32 v81, v76
	v_lshlrev_b64 v[76:77], 6, v[82:83]
	v_lshl_add_u64 v[76:77], v[160:161], 0, v[76:77]
	global_load_dwordx4 v[218:221], v[76:77], off
	flat_store_dwordx4 v[80:81], v[66:69]
	flat_store_dwordx4 v[80:81], v[70:73] offset:64
	s_waitcnt vmcnt(2)
	flat_store_dwordx4 v[80:81], v[218:221] offset:128

;     __device__ __forceinline__ void operator()(const f32x4 (&acc)[2][2][4][2], const Unit& u, int wr, int wc, int fr, int fq) const {
;     ...
;                 const size_t hs = (size_t)(b * 4 + h) * SEQ + s_;
;                 if (isq) { bf16_t* d = QB + hs * 96;
;                     if (!rope) { *(u32x4*)(d + 8 * fq) = wa; *(u32x4*)(d + 32 + 8 * fq) = wb; }
;                     else if (fq < 2) { *(u32x4*)(d + 64 + 8 * fq) = wa; *(u32x4*)(d + 80 + 8 * fq) = wb; } }
;                 else if (!isv) { bf16_t* d = KB + hs * 96; *(u32x4*)(d + 8 * fq) = wa; *(u32x4*)(d + 32 + 8 * fq) = wb;
;                     *(u32x4*)(d + 64 + 8 * fq) = *(const u32x4*)(KPE + (size_t)row * 32 + 8 * fq); }
.LBB0_559:
	s_andn2_b64 vcc, exec, s[72:73]
	s_cbranch_vccnz .LBB0_561
	s_movk_i32 s2, 0xc0
	v_mad_u64_u32 v[52:53], s[72:73], v50, s2, v[164:165]
	v_mov_b32_e32 v16, v53
	v_mad_u64_u32 v[62:63], s[72:73], v51, s2, v[16:17]
	v_ashrrev_i32_e32 v67, 31, v66
	v_mov_b32_e32 v53, v62
	v_lshlrev_b64 v[62:63], 6, v[66:67]
	v_lshl_add_u64 v[62:63], v[160:161], 0, v[62:63]
	global_load_dwordx4 v[218:221], v[62:63], off
	flat_store_dwordx4 v[52:53], v[34:37]
	flat_store_dwordx4 v[52:53], v[42:45] offset:64
	s_waitcnt vmcnt(2)
	flat_store_dwordx4 v[52:53], v[218:221] offset:128

;     __device__ __forceinline__ void operator()(const f32x4 (&acc)[2][2][4][2], const Unit& u, int wr, int wc, int fr, int fq) const {
;     ...
;                 const size_t hs = (size_t)(b * 4 + h) * SEQ + s_;
;                 if (isq) { bf16_t* d = QB + hs * 96;
;                     if (!rope) { *(u32x4*)(d + 8 * fq) = wa; *(u32x4*)(d + 32 + 8 * fq) = wb; }
;                     else if (fq < 2) { *(u32x4*)(d + 64 + 8 * fq) = wa; *(u32x4*)(d + 80 + 8 * fq) = wb; } }
;                 else if (!isv) { bf16_t* d = KB + hs * 96; *(u32x4*)(d + 8 * fq) = wa; *(u32x4*)(d + 32 + 8 * fq) = wb;
;                     *(u32x4*)(d + 64 + 8 * fq) = *(const u32x4*)(KPE + (size_t)row * 32 + 8 * fq); }
.LBB0_577:
	s_andn2_b64 vcc, exec, s[72:73]
	s_cbranch_vccnz .LBB0_579
	s_movk_i32 s2, 0xc0
	v_mad_u64_u32 v[32:33], s[72:73], v26, s2, v[164:165]
	v_mov_b32_e32 v16, v33
	v_mad_u64_u32 v[28:29], s[72:73], v27, s2, v[16:17]
	v_ashrrev_i32_e32 v35, 31, v34
	v_mov_b32_e32 v33, v28
	v_lshlrev_b64 v[28:29], 6, v[34:35]
	v_lshl_add_u64 v[28:29], v[160:161], 0, v[28:29]
	global_load_dwordx4 v[218:221], v[28:29], off
	flat_store_dwordx4 v[32:33], v[18:21]
	flat_store_dwordx4 v[32:33], v[22:25] offset:64
	s_waitcnt vmcnt(2)
	flat_store_dwordx4 v[32:33], v[218:221] offset:128

;     __device__ __forceinline__ void operator()(const f32x4 (&acc)[2][2][4][2], const Unit& u, int wr, int wc, int fr, int fq) const {
;     ...
;                 const size_t hs = (size_t)(b * 4 + h) * SEQ + s_;
;                 if (isq) { bf16_t* d = QB + hs * 96;
;                     if (!rope) { *(u32x4*)(d + 8 * fq) = wa; *(u32x4*)(d + 32 + 8 * fq) = wb; }
;                     else if (fq < 2) { *(u32x4*)(d + 64 + 8 * fq) = wa; *(u32x4*)(d + 80 + 8 * fq) = wb; } }
;                 else if (!isv) { bf16_t* d = KB + hs * 96; *(u32x4*)(d + 8 * fq) = wa; *(u32x4*)(d + 32 + 8 * fq) = wb;
;                     *(u32x4*)(d + 64 + 8 * fq) = *(const u32x4*)(KPE + (size_t)row * 32 + 8 * fq); }
.LBB0_595:
	s_andn2_b64 vcc, exec, s[0:1]
	s_cbranch_vccnz .LBB0_597
	s_movk_i32 s2, 0xc0
	v_mad_u64_u32 v[14:15], s[0:1], v8, s2, v[164:165]
	v_mov_b32_e32 v10, v15
	v_mad_u64_u32 v[10:11], s[0:1], v9, s2, v[10:11]
	v_ashrrev_i32_e32 v19, 31, v18
	v_mov_b32_e32 v15, v10
	v_lshlrev_b64 v[10:11], 6, v[18:19]
	v_lshl_add_u64 v[10:11], v[160:161], 0, v[10:11]
	global_load_dwordx4 v[218:221], v[10:11], off
	flat_store_dwordx4 v[14:15], v[0:3]
	flat_store_dwordx4 v[14:15], v[4:7] offset:64
	s_waitcnt vmcnt(2)
	flat_store_dwordx4 v[14:15], v[218:221] offset:128
